# S5: states go to the output MFMA through a packed bf16 LDS image (half the LDS bytes), recurrence as 2-level scalar FMA chain; plus snake MFMA order + tail 2
# baseline (speedup 1.0000x reference)
; __device__ __forceinline__ unsigned cvtpk(float lo, float hi) { f32x2_t v = {lo, hi}; bf16x2_t b = __builtin_convertvector(v, bf16x2_t); return __builtin_bit_cast(unsigned, b); }
; __device__ __forceinline__ void s5_task(const Args& a, const bf16_t* XN, const float* SS, bf16_t* Y, LAS float* S, int b, int g, int lane) {
;     ...
;     for (int ct = 0; ct < 8; ++ct) { unsigned w[4];
; #pragma unroll
;         for (int jj = 0; jj < 4; ++jj) { float v[2];
; #pragma unroll
;             for (int e = 0; e < 2; ++e) { const float x = BT[((size_t)g * 16 + 8 * (j4 & 1) + 2 * jj + e) * 128 + 8 * n16 + ct]; const float hi = __uint_as_float(cvtpk(x, 0.f) << 16); v[e] = (j4 < 2) ? x : (x - hi); }
;             w[jj] = cvtpk(v[0], v[1]); }
;         bw[ct] = __builtin_bit_cast(bf16x8, (u32x4){w[0], w[1], w[2], w[3]}); }
; #pragma unroll
;     for (int kk = 0; kk < 4; ++kk) { unsigned w[4];
; #pragma unroll
;         for (int jj = 0; jj < 4; ++jj) w[jj] = cvtpk(CT[((size_t)g * 128 + 32 * kk + 8 * j4 + 2 * jj) * 16 + n16], CT[((size_t)g * 128 + 32 * kk + 8 * j4 + 2 * jj + 1) * 16 + n16]);
;         cw[kk] = __builtin_bit_cast(bf16x8, (u32x4){w[0], w[1], w[2], w[3]}); }
;     bf16x8 dw;
;     { unsigned w[4];
; #pragma unroll
;       for (int jj = 0; jj < 4; ++jj) { float v[2];
; #pragma unroll
;           for (int e = 0; e < 2; ++e) { const int c = 8 * (j4 & 1) + 2 * jj + e; const float x = (c == n16) ? a.in[18][g * 16 + n16] : 0.f; const float hi = __uint_as_float(cvtpk(x, 0.f) << 16); v[e] = (j4 < 2) ? x : (x - hi); }
;           w[jj] = cvtpk(v[0], v[1]); }
;       dw = __builtin_bit_cast(bf16x8, (u32x4){w[0], w[1], w[2], w[3]}); }
.LBB0_665:
	s_or_b64 exec, exec, s[28:29]
	s_waitcnt vmcnt(0)
	v_cvt_pk_bf16_f32 v0, v9, 0
	v_lshlrev_b32_e32 v0, 16, v0
	v_sub_f32_e32 v0, v9, v0
	v_cndmask_b32_e32 v147, v0, v9, vcc
	v_cvt_pk_bf16_f32 v0, v2, 0
	v_cvt_pk_bf16_f32 v1, v8, 0
	v_lshlrev_b32_e32 v0, 16, v0
	v_lshlrev_b32_e32 v1, 16, v1
	v_sub_f32_e32 v0, v2, v0
	v_sub_f32_e32 v1, v8, v1
	v_cndmask_b32_e32 v0, v0, v2, vcc
	v_cndmask_b32_e32 v1, v1, v8, vcc
	v_cvt_pk_bf16_f32 v2, v0, v1
	v_cvt_pk_bf16_f32 v0, v6, 0
	v_cvt_pk_bf16_f32 v1, v7, 0
	v_lshlrev_b32_e32 v0, 16, v0
	v_lshlrev_b32_e32 v1, 16, v1
	v_sub_f32_e32 v0, v6, v0
	v_sub_f32_e32 v1, v7, v1
	v_cndmask_b32_e32 v0, v0, v6, vcc
	v_cndmask_b32_e32 v1, v1, v7, vcc
	v_cvt_pk_bf16_f32 v1, v0, v1
	v_cvt_pk_bf16_f32 v0, v4, 0
	v_lshlrev_b32_e32 v0, 16, v0
	v_sub_f32_e32 v0, v4, v0
	v_cndmask_b32_e32 v0, v0, v4, vcc
	v_cvt_pk_bf16_f32 v4, v5, 0
	v_lshlrev_b32_e32 v4, 16, v4
	v_sub_f32_e32 v4, v5, v4
	v_cndmask_b32_e32 v4, v4, v5, vcc
	v_cvt_pk_bf16_f32 v0, v0, v4
	v_cvt_pk_bf16_f32 v4, v74, 0
	v_cvt_pk_bf16_f32 v5, v78, 0
	v_lshlrev_b32_e32 v4, 16, v4
	v_lshlrev_b32_e32 v5, 16, v5
	v_sub_f32_e32 v4, v74, v4
	v_sub_f32_e32 v5, v78, v5
	v_cndmask_b32_e32 v4, v4, v74, vcc
	v_cndmask_b32_e32 v5, v5, v78, vcc
	v_cvt_pk_bf16_f32 v4, v4, v5
	v_cvt_pk_bf16_f32 v5, v66, 0
	v_cvt_pk_bf16_f32 v6, v70, 0
	v_lshlrev_b32_e32 v5, 16, v5
	v_lshlrev_b32_e32 v6, 16, v6
	v_sub_f32_e32 v5, v66, v5
	v_sub_f32_e32 v6, v70, v6
	v_cndmask_b32_e32 v5, v5, v66, vcc
	v_cndmask_b32_e32 v6, v6, v70, vcc
	v_cvt_pk_bf16_f32 v5, v5, v6
	v_cvt_pk_bf16_f32 v6, v40, 0
	v_cvt_pk_bf16_f32 v7, v44, 0
	v_lshlrev_b32_e32 v6, 16, v6
	v_lshlrev_b32_e32 v7, 16, v7
	v_sub_f32_e32 v6, v40, v6
	v_sub_f32_e32 v7, v44, v7
	v_cndmask_b32_e32 v6, v6, v40, vcc
	v_cndmask_b32_e32 v7, v7, v44, vcc
	v_cvt_pk_bf16_f32 v6, v6, v7
	v_cvt_pk_bf16_f32 v7, v16, 0
	v_cvt_pk_bf16_f32 v8, v20, 0
	v_lshlrev_b32_e32 v7, 16, v7
	v_lshlrev_b32_e32 v8, 16, v8
	v_sub_f32_e32 v7, v16, v7
	v_sub_f32_e32 v8, v20, v8
	v_cndmask_b32_e32 v7, v7, v16, vcc
	v_cndmask_b32_e32 v8, v8, v20, vcc
	v_cvt_pk_bf16_f32 v7, v7, v8
	v_cvt_pk_bf16_f32 v8, v75, 0
	v_cvt_pk_bf16_f32 v9, v79, 0
	v_lshlrev_b32_e32 v8, 16, v8
	v_lshlrev_b32_e32 v9, 16, v9
	v_sub_f32_e32 v8, v75, v8
	v_sub_f32_e32 v9, v79, v9
	v_cndmask_b32_e32 v8, v8, v75, vcc
	v_cndmask_b32_e32 v9, v9, v79, vcc
	v_cvt_pk_bf16_f32 v8, v8, v9
	v_cvt_pk_bf16_f32 v9, v67, 0
	v_cvt_pk_bf16_f32 v10, v71, 0
	v_lshlrev_b32_e32 v9, 16, v9
	v_lshlrev_b32_e32 v10, 16, v10
	v_sub_f32_e32 v9, v67, v9
	v_sub_f32_e32 v10, v71, v10
	v_cndmask_b32_e32 v9, v9, v67, vcc
	v_cndmask_b32_e32 v10, v10, v71, vcc
	v_cvt_pk_bf16_f32 v9, v9, v10
	v_cvt_pk_bf16_f32 v10, v41, 0
	v_cvt_pk_bf16_f32 v11, v45, 0
	v_lshlrev_b32_e32 v10, 16, v10
	v_lshlrev_b32_e32 v11, 16, v11
	v_sub_f32_e32 v10, v41, v10
	v_sub_f32_e32 v11, v45, v11
	v_cndmask_b32_e32 v10, v10, v41, vcc
	v_cndmask_b32_e32 v11, v11, v45, vcc
	v_cvt_pk_bf16_f32 v10, v10, v11
	v_cvt_pk_bf16_f32 v11, v17, 0
	v_cvt_pk_bf16_f32 v12, v21, 0
	v_lshlrev_b32_e32 v11, 16, v11
	v_lshlrev_b32_e32 v12, 16, v12
	v_sub_f32_e32 v11, v17, v11
	v_sub_f32_e32 v12, v21, v12
	v_cndmask_b32_e32 v11, v11, v17, vcc
	v_cndmask_b32_e32 v12, v12, v21, vcc
	v_cvt_pk_bf16_f32 v11, v11, v12
	v_cvt_pk_bf16_f32 v12, v76, 0
	v_cvt_pk_bf16_f32 v13, v80, 0
	v_lshlrev_b32_e32 v12, 16, v12
	v_lshlrev_b32_e32 v13, 16, v13
	v_sub_f32_e32 v12, v76, v12
	v_sub_f32_e32 v13, v80, v13
	v_cndmask_b32_e32 v12, v12, v76, vcc
	v_cndmask_b32_e32 v13, v13, v80, vcc
	v_cvt_pk_bf16_f32 v12, v12, v13
	v_cvt_pk_bf16_f32 v13, v68, 0
	v_cvt_pk_bf16_f32 v14, v72, 0
	v_lshlrev_b32_e32 v13, 16, v13
	v_lshlrev_b32_e32 v14, 16, v14
	v_sub_f32_e32 v13, v68, v13
	v_sub_f32_e32 v14, v72, v14
	v_cndmask_b32_e32 v13, v13, v68, vcc
	v_cndmask_b32_e32 v14, v14, v72, vcc
	v_cvt_pk_bf16_f32 v13, v13, v14
	v_cvt_pk_bf16_f32 v14, v42, 0
	v_cvt_pk_bf16_f32 v15, v46, 0
	v_lshlrev_b32_e32 v14, 16, v14
	v_lshlrev_b32_e32 v15, 16, v15
	v_sub_f32_e32 v14, v42, v14
	v_sub_f32_e32 v15, v46, v15
	v_cndmask_b32_e32 v14, v14, v42, vcc
	v_cndmask_b32_e32 v15, v15, v46, vcc
	v_cvt_pk_bf16_f32 v14, v14, v15
	v_cvt_pk_bf16_f32 v15, v18, 0
	v_cvt_pk_bf16_f32 v16, v22, 0
	v_lshlrev_b32_e32 v15, 16, v15
	v_lshlrev_b32_e32 v16, 16, v16
	v_sub_f32_e32 v15, v18, v15
	v_sub_f32_e32 v16, v22, v16
	v_cndmask_b32_e32 v15, v15, v18, vcc
	v_cndmask_b32_e32 v16, v16, v22, vcc
	v_cvt_pk_bf16_f32 v15, v15, v16
	v_cvt_pk_bf16_f32 v16, v77, 0
	v_cvt_pk_bf16_f32 v17, v81, 0
	v_lshlrev_b32_e32 v16, 16, v16
	v_lshlrev_b32_e32 v17, 16, v17
	v_sub_f32_e32 v16, v77, v16
	v_sub_f32_e32 v17, v81, v17
	v_cndmask_b32_e32 v16, v16, v77, vcc
	v_cndmask_b32_e32 v17, v17, v81, vcc
	v_cvt_pk_bf16_f32 v16, v16, v17
	v_cvt_pk_bf16_f32 v17, v69, 0
	v_cvt_pk_bf16_f32 v18, v73, 0
	v_lshlrev_b32_e32 v17, 16, v17
	v_lshlrev_b32_e32 v18, 16, v18
	v_sub_f32_e32 v17, v69, v17
	v_sub_f32_e32 v18, v73, v18
	v_cndmask_b32_e32 v17, v17, v69, vcc
	v_cndmask_b32_e32 v18, v18, v73, vcc
	v_cvt_pk_bf16_f32 v17, v17, v18
	v_cvt_pk_bf16_f32 v18, v43, 0
	v_cvt_pk_bf16_f32 v20, v47, 0
	v_lshlrev_b32_e32 v18, 16, v18
	v_lshlrev_b32_e32 v20, 16, v20
	v_sub_f32_e32 v18, v43, v18
	v_sub_f32_e32 v20, v47, v20
	v_cndmask_b32_e32 v18, v18, v43, vcc
	v_cndmask_b32_e32 v20, v20, v47, vcc
	v_cvt_pk_bf16_f32 v18, v18, v20
	v_cvt_pk_bf16_f32 v20, v19, 0
	v_lshlrev_b32_e32 v20, 16, v20
	v_sub_f32_e32 v20, v19, v20
	v_cndmask_b32_e32 v19, v20, v19, vcc
	v_cvt_pk_bf16_f32 v20, v23, 0
	v_lshlrev_b32_e32 v20, 16, v20
	v_sub_f32_e32 v20, v23, v20
	v_cndmask_b32_e32 v20, v20, v23, vcc
	v_cvt_pk_bf16_f32 v19, v19, v20
	v_cvt_pk_bf16_f32 v20, v54, 0
	v_cvt_pk_bf16_f32 v21, v58, 0
; __device__ __forceinline__ unsigned cvtpk(float lo, float hi) { f32x2_t v = {lo, hi}; bf16x2_t b = __builtin_convertvector(v, bf16x2_t); return __builtin_bit_cast(unsigned, b); }
; #define LAS __attribute__((address_space(3)))
; __device__ __forceinline__ void s5_task(const Args& a, const bf16_t* XN, const float* SS, bf16_t* Y, LAS float* S, int b, int g, int lane) {
;     ...
;     for (int ct = 0; ct < 8; ++ct) { unsigned w[4];
; #pragma unroll
;         for (int jj = 0; jj < 4; ++jj) { float v[2];
; #pragma unroll
;             for (int e = 0; e < 2; ++e) { const float x = BT[((size_t)g * 16 + 8 * (j4 & 1) + 2 * jj + e) * 128 + 8 * n16 + ct]; const float hi = __uint_as_float(cvtpk(x, 0.f) << 16); v[e] = (j4 < 2) ? x : (x - hi); }
;             w[jj] = cvtpk(v[0], v[1]); }
;         bw[ct] = __builtin_bit_cast(bf16x8, (u32x4){w[0], w[1], w[2], w[3]}); }
; #pragma unroll
;     for (int kk = 0; kk < 4; ++kk) { unsigned w[4];
; #pragma unroll
;         for (int jj = 0; jj < 4; ++jj) w[jj] = cvtpk(CT[((size_t)g * 128 + 32 * kk + 8 * j4 + 2 * jj) * 16 + n16], CT[((size_t)g * 128 + 32 * kk + 8 * j4 + 2 * jj + 1) * 16 + n16]);
;         cw[kk] = __builtin_bit_cast(bf16x8, (u32x4){w[0], w[1], w[2], w[3]}); }
;     bf16x8 dw;
;     { unsigned w[4];
; #pragma unroll
;       for (int jj = 0; jj < 4; ++jj) { float v[2];
; #pragma unroll
;           for (int e = 0; e < 2; ++e) { const int c = 8 * (j4 & 1) + 2 * jj + e; const float x = (c == n16) ? a.in[18][g * 16 + n16] : 0.f; const float hi = __uint_as_float(cvtpk(x, 0.f) << 16); v[e] = (j4 < 2) ? x : (x - hi); }
;           w[jj] = cvtpk(v[0], v[1]); }
;       dw = __builtin_bit_cast(bf16x8, (u32x4){w[0], w[1], w[2], w[3]}); }
;     float sre = 0.f, sim = 0.f;
;     const size_t rowb = (size_t)b * SEQ;
;     LAS unsigned short* YS = (LAS unsigned short*)(S + 16 * 132);
;     u32x4 unext = *(const u32x4*)(XN + (rowb + n16) * DM + 16 * g + 8 * (j4 & 1));
;     float ssn = SS[rowb + n16];
	v_lshlrev_b32_e32 v20, 16, v20
	v_lshlrev_b32_e32 v21, 16, v21
	v_sub_f32_e32 v20, v54, v20
	v_sub_f32_e32 v21, v58, v21
	v_cndmask_b32_e32 v20, v20, v54, vcc
	v_cndmask_b32_e32 v21, v21, v58, vcc
	v_cvt_pk_bf16_f32 v20, v20, v21
	v_cvt_pk_bf16_f32 v21, v36, 0
	v_cvt_pk_bf16_f32 v22, v50, 0
	v_lshlrev_b32_e32 v21, 16, v21
	v_lshlrev_b32_e32 v22, 16, v22
	v_sub_f32_e32 v21, v36, v21
	v_sub_f32_e32 v22, v50, v22
	v_cndmask_b32_e32 v21, v21, v36, vcc
	v_cndmask_b32_e32 v22, v22, v50, vcc
	v_cvt_pk_bf16_f32 v21, v21, v22
	v_cvt_pk_bf16_f32 v22, v28, 0
	v_cvt_pk_bf16_f32 v23, v32, 0
	v_lshlrev_b32_e32 v22, 16, v22
	v_lshlrev_b32_e32 v23, 16, v23
	v_sub_f32_e32 v22, v28, v22
	v_sub_f32_e32 v23, v32, v23
	v_cndmask_b32_e32 v22, v22, v28, vcc
	v_cndmask_b32_e32 v23, v23, v32, vcc
	v_cvt_pk_bf16_f32 v22, v22, v23
	v_cvt_pk_bf16_f32 v23, v24, 0
	v_lshlrev_b32_e32 v23, 16, v23
	v_sub_f32_e32 v23, v24, v23
	v_cndmask_b32_e32 v23, v23, v24, vcc
	v_cvt_pk_bf16_f32 v24, v62, 0
	v_lshlrev_b32_e32 v24, 16, v24
	v_sub_f32_e32 v24, v62, v24
	v_cndmask_b32_e32 v24, v24, v62, vcc
	v_cvt_pk_bf16_f32 v23, v23, v24
	v_cvt_pk_bf16_f32 v24, v55, 0
	v_cvt_pk_bf16_f32 v28, v59, 0
	v_lshlrev_b32_e32 v24, 16, v24
	v_lshlrev_b32_e32 v28, 16, v28
	v_sub_f32_e32 v24, v55, v24
	v_sub_f32_e32 v28, v59, v28
	v_cndmask_b32_e32 v24, v24, v55, vcc
	v_cndmask_b32_e32 v28, v28, v59, vcc
	v_cvt_pk_bf16_f32 v40, v24, v28
	v_cvt_pk_bf16_f32 v24, v37, 0
	v_cvt_pk_bf16_f32 v28, v51, 0
	v_lshlrev_b32_e32 v24, 16, v24
	v_lshlrev_b32_e32 v28, 16, v28
	v_sub_f32_e32 v24, v37, v24
	v_sub_f32_e32 v28, v51, v28
	v_cndmask_b32_e32 v24, v24, v37, vcc
	v_cndmask_b32_e32 v28, v28, v51, vcc
	v_cvt_pk_bf16_f32 v41, v24, v28
	v_cvt_pk_bf16_f32 v24, v29, 0
	v_cvt_pk_bf16_f32 v28, v33, 0
	v_lshlrev_b32_e32 v24, 16, v24
	v_lshlrev_b32_e32 v28, 16, v28
	v_sub_f32_e32 v24, v29, v24
	v_sub_f32_e32 v28, v33, v28
	v_cndmask_b32_e32 v24, v24, v29, vcc
	v_cndmask_b32_e32 v28, v28, v33, vcc
	v_cvt_pk_bf16_f32 v42, v24, v28
	v_cvt_pk_bf16_f32 v24, v25, 0
	v_lshlrev_b32_e32 v24, 16, v24
	v_sub_f32_e32 v24, v25, v24
	v_cndmask_b32_e32 v24, v24, v25, vcc
	v_cvt_pk_bf16_f32 v25, v63, 0
	v_lshlrev_b32_e32 v25, 16, v25
	v_sub_f32_e32 v25, v63, v25
	v_cndmask_b32_e32 v25, v25, v63, vcc
	v_cvt_pk_bf16_f32 v43, v24, v25
	v_cvt_pk_bf16_f32 v24, v56, 0
	v_cvt_pk_bf16_f32 v25, v60, 0
	v_lshlrev_b32_e32 v24, 16, v24
	v_lshlrev_b32_e32 v25, 16, v25
	v_sub_f32_e32 v24, v56, v24
	v_sub_f32_e32 v25, v60, v25
	v_cndmask_b32_e32 v24, v24, v56, vcc
	v_cndmask_b32_e32 v25, v25, v60, vcc
	v_cvt_pk_bf16_f32 v44, v24, v25
	v_cvt_pk_bf16_f32 v24, v38, 0
	v_cvt_pk_bf16_f32 v25, v52, 0
	v_lshlrev_b32_e32 v24, 16, v24
	v_lshlrev_b32_e32 v25, 16, v25
	v_sub_f32_e32 v24, v38, v24
	v_sub_f32_e32 v25, v52, v25
	s_and_b32 s28, s43, 0x7f
	v_cndmask_b32_e32 v24, v24, v38, vcc
	v_cndmask_b32_e32 v25, v25, v52, vcc
	s_lshl_b32 s59, s28, 5
	s_add_i32 s28, s56, s35
	v_cvt_pk_bf16_f32 v45, v24, v25
	v_cvt_pk_bf16_f32 v24, v30, 0
	v_cvt_pk_bf16_f32 v25, v34, 0
	s_ashr_i32 s28, s28, 7
	v_lshlrev_b32_e32 v24, 16, v24
	v_lshlrev_b32_e32 v25, 16, v25
	v_sub_f32_e32 v24, v30, v24
	v_sub_f32_e32 v25, v34, v25
	s_ashr_i32 s29, s28, 31
	v_cndmask_b32_e32 v24, v24, v30, vcc
	v_cndmask_b32_e32 v25, v25, v34, vcc
	s_lshl_b64 s[68:69], s[28:29], 11
	v_cvt_pk_bf16_f32 v46, v24, v25
	v_mov_b32_e32 v25, s69
	v_or_b32_e32 v24, s68, v82
	v_lshlrev_b64 v[28:29], 12, v[24:25]
	v_lshl_add_u64 v[28:29], s[40:41], 0, v[28:29]
	s_lshl_b32 s38, s57, 1
	v_lshl_add_u64 v[28:29], v[28:29], 0, s[38:39]
	v_lshlrev_b32_e32 v88, 1, v86
	v_lshl_add_u64 v[28:29], v[28:29], 0, v[88:89]
	v_lshl_add_u64 v[24:25], v[24:25], 2, s[62:63]
	global_load_dwordx4 v[48:51], v[28:29], off
	global_load_dword v124, v[24:25], off
	v_cvt_pk_bf16_f32 v24, v26, 0
	v_cvt_pk_bf16_f32 v25, v64, 0
	v_lshlrev_b32_e32 v24, 16, v24
	v_lshlrev_b32_e32 v25, 16, v25
	v_sub_f32_e32 v24, v26, v24
	v_sub_f32_e32 v25, v64, v25
	v_cndmask_b32_e32 v24, v24, v26, vcc
	v_cndmask_b32_e32 v25, v25, v64, vcc
	v_cvt_pk_bf16_f32 v47, v24, v25
	v_cvt_pk_bf16_f32 v24, v57, 0
	v_cvt_pk_bf16_f32 v25, v61, 0
	v_lshlrev_b32_e32 v24, 16, v24
	v_lshlrev_b32_e32 v25, 16, v25
	v_sub_f32_e32 v24, v57, v24
	v_sub_f32_e32 v25, v61, v25
	v_cndmask_b32_e32 v24, v24, v57, vcc
	v_cndmask_b32_e32 v25, v25, v61, vcc
	v_cvt_pk_bf16_f32 v52, v24, v25
	v_cvt_pk_bf16_f32 v24, v39, 0
	v_cvt_pk_bf16_f32 v25, v53, 0
	v_lshlrev_b32_e32 v24, 16, v24
	v_lshlrev_b32_e32 v25, 16, v25
	v_sub_f32_e32 v24, v39, v24
	v_sub_f32_e32 v25, v53, v25
	v_cndmask_b32_e32 v24, v24, v39, vcc
	v_cndmask_b32_e32 v25, v25, v53, vcc
	v_cvt_pk_bf16_f32 v53, v24, v25
	v_cvt_pk_bf16_f32 v24, v31, 0
	v_cvt_pk_bf16_f32 v25, v35, 0
	v_lshlrev_b32_e32 v24, 16, v24
	v_lshlrev_b32_e32 v25, 16, v25
	v_sub_f32_e32 v24, v31, v24
	v_sub_f32_e32 v25, v35, v25
	v_cndmask_b32_e32 v24, v24, v31, vcc
	v_cndmask_b32_e32 v25, v25, v35, vcc
	v_cvt_pk_bf16_f32 v54, v24, v25
	v_cvt_pk_bf16_f32 v24, v27, 0
	v_cvt_pk_bf16_f32 v25, v65, 0
	v_cvt_pk_bf16_f32 v36, v3, v105
	v_cvt_pk_bf16_f32 v3, v146, 0
	v_lshlrev_b32_e32 v24, 16, v24
	v_lshlrev_b32_e32 v25, 16, v25
	v_lshlrev_b32_e32 v3, 16, v3
	v_sub_f32_e32 v24, v27, v24
	v_sub_f32_e32 v25, v65, v25
	v_sub_f32_e32 v3, v146, v3
	s_lshl_b64 s[60:61], s[28:29], 13
	s_lshl_b64 s[28:29], s[28:29], 23
	v_cndmask_b32_e32 v24, v24, v27, vcc
	v_cndmask_b32_e32 v25, v25, v65, vcc
	v_cndmask_b32_e32 v3, v3, v146, vcc
	s_or_b32 s28, s28, s59
	v_cvt_pk_bf16_f32 v55, v24, v25
	v_cvt_pk_bf16_f32 v37, v106, v107
	v_cvt_pk_bf16_f32 v38, v108, v109
	v_cvt_pk_bf16_f32 v39, v110, v111
	v_cvt_pk_bf16_f32 v32, v112, v114
	v_cvt_pk_bf16_f32 v33, v123, v125
	v_cvt_pk_bf16_f32 v34, v126, v127
	v_cvt_pk_bf16_f32 v35, v128, v129
	v_cvt_pk_bf16_f32 v28, v130, v131
	v_cvt_pk_bf16_f32 v29, v132, v133
	v_cvt_pk_bf16_f32 v30, v134, v135
	v_cvt_pk_bf16_f32 v31, v136, v137
	v_cvt_pk_bf16_f32 v24, v138, v139
	v_cvt_pk_bf16_f32 v25, v140, v141
	v_cvt_pk_bf16_f32 v26, v142, v143
	v_cvt_pk_bf16_f32 v27, v144, v145
	v_cvt_pk_bf16_f32 v3, v147, v3
	v_mov_b32_e32 v76, v102
	v_mov_b32_e32 v77, v102
	v_mov_b32_e32 v78, v103
	v_mov_b32_e32 v79, v103
	v_pk_mov_b32 v[80:81], v[102:103], v[102:103] op_sel:[1,0]
	v_lshl_add_u64 v[106:107], v[96:97], 0, s[60:61]
	v_lshl_add_u64 v[108:109], v[98:99], 0, s[28:29]
	v_lshl_add_u64 v[110:111], v[100:101], 0, s[28:29]
	s_mov_b64 s[28:29], 0
	v_mov_b32_e32 v105, v104
	v_lshl_add_u32 v208, v206, 2, s48
	v_add_u32_e32 v208, 0x12000, v208
	v_and_b32_e32 v209, 15, v206
	v_lshrrev_b32_e32 v210, 4, v206
	v_mul_u32_u24_e32 v209, 0x110, v209
	v_lshl_add_u32 v209, v210, 4, v209
	v_add_u32_e32 v207, s48, v209
	v_add_u32_e32 v207, 0x12000, v207
	s_waitcnt vmcnt(0)
; __device__ __forceinline__ float rs_of(float ss) { return __builtin_amdgcn_rsqf(ss * (1.0f / 2048.0f) + 1e-6f); }
; #define LAS __attribute__((address_space(3)))
; #define LDS_WAIT() asm volatile("s_waitcnt lgkmcnt(0)" ::: "memory")
; #define MFMA16(a, b, c) __builtin_amdgcn_mfma_f32_16x16x32_bf16((a), (b), (c), 0, 0, 0)
; __device__ __forceinline__ void s5_task(const Args& a, const bf16_t* XN, const float* SS, bf16_t* Y, LAS float* S, int b, int g, int lane) {
;     ...
;     for (int blk = 0; blk < SEQ / 16; ++blk) {
;         const size_t row0 = rowb + blk * 16;
;         const u32x4 uraw = unext; const float rsl = rs_of(ssn);
;         { const size_t rn = (blk + 1 < SEQ / 16) ? row0 + 16 : row0;
;           unext = *(const u32x4*)(XN + (rn + n16) * DM + 16 * g + 8 * (j4 & 1)); ssn = SS[rn + n16]; }
;         float rsw[4];
; #pragma unroll
;         for (int i = 0; i < 4; ++i) rsw[i] = __shfl(rsl, 4 * j4 + i);
;         const bf16x8 ua = __builtin_bit_cast(bf16x8, uraw);
;         f32x4 bu[8];
; #pragma unroll
;         for (int ct = 0; ct < 8; ++ct) bu[ct] = MFMA16(ua, bw[ct], ((f32x4){0.f, 0.f, 0.f, 0.f}));
;         const f32x4 yd = MFMA16(ua, dw, ((f32x4){0.f, 0.f, 0.f, 0.f}));
; #pragma unroll
;         for (int i = 0; i < 4; ++i) { LAS float* w = S + (4 * j4 + i) * 132 + 8 * n16; const float q = rsw[i];
;             *(LAS f32x4*)w = (f32x4){bu[0][i] * q, bu[1][i] * q, bu[2][i] * q, bu[3][i] * q}; *(LAS f32x4*)(w + 4) = (f32x4){bu[4][i] * q, bu[5][i] * q, bu[6][i] * q, bu[7][i] * q}; }
;         LDS_WAIT();
; #pragma unroll
;         for (int tt = 0; tt < 16; ++tt) { LAS f32x2* sp = (LAS f32x2*)(S + tt * 132 + 2 * lane); const f32x2 v = *sp;
;             const float nre = ar * sre - ai * sim + v.x, nim = ar * sim + ai * sre + v.y; sre = nre; sim = nim; *sp = (f32x2){sre, sim}; }
.LBB0_666:
	s_waitcnt vmcnt(1)
	v_mov_b64_e32 v[74:75], v[50:51]
	v_mov_b64_e32 v[72:73], v[48:49]
	s_waitcnt vmcnt(1)
	v_fmamk_f32 v50, v124, 0x3a000000, v119
	v_rsq_f32_e32 v88, v50
	v_pk_mul_f32 v[126:127], v[80:81], v[104:105] op_sel:[0,1]
	v_lshl_add_u64 v[48:49], v[108:109], 0, s[28:29]
	v_mfma_f32_16x16x32_bf16 v[64:67], v[72:75], v[4:7], 0
	ds_bpermute_b32 v154, v113, v88
	ds_bpermute_b32 v114, v115, v88
	ds_bpermute_b32 v112, v116, v88
	v_mfma_f32_16x16x32_bf16 v[56:59], v[72:75], v[8:11], 0
	ds_bpermute_b32 v88, v117, v88
	v_pk_fma_f32 v[152:153], v[102:103], v[104:105], v[126:127] neg_lo:[0,0,1] neg_hi:[0,0,1]
	v_pk_fma_f32 v[104:105], v[102:103], v[104:105], v[126:127] op_sel_hi:[1,0,1]
	v_mfma_f32_16x16x32_bf16 v[68:71], v[72:75], v[12:15], 0
	v_mov_b32_e32 v153, v105
	v_mov_b32_e32 v104, v64
	s_nop 1
	v_mov_b32_e32 v105, v56
	v_mfma_f32_16x16x32_bf16 v[60:63], v[72:75], v[16:19], 0
	v_mov_b32_e32 v56, v65
	s_nop 0
	v_mov_b32_e32 v144, v68
	v_mov_b32_e32 v150, v66
	v_mfma_f32_16x16x32_bf16 v[128:131], v[72:75], v[20:23], 0
	v_mov_b32_e32 v151, v58
	s_nop 1
	v_mov_b32_e32 v145, v60
	v_mov_b32_e32 v60, v69
	v_mfma_f32_16x16x32_bf16 v[132:135], v[72:75], v[40:43], 0
	v_mov_b32_e32 v156, v70
	s_nop 0
	v_mov_b32_e32 v146, v128
	v_mov_b32_e32 v157, v62
	v_mfma_f32_16x16x32_bf16 v[136:139], v[72:75], v[44:47], 0
	v_mov_b32_e32 v158, v130
	s_nop 1
	v_mov_b32_e32 v147, v132
	v_mov_b32_e32 v132, v129
	v_mfma_f32_16x16x32_bf16 v[140:143], v[72:75], v[52:55], 0
	v_mov_b32_e32 v159, v134
	s_nop 0
	v_mov_b32_e32 v148, v136
	v_mov_b32_e32 v172, v138
	v_mov_b32_e32 v58, v67
	v_mov_b32_e32 v62, v71
	s_nop 1
	v_mov_b32_e32 v149, v140
	v_mov_b32_e32 v140, v137
	v_mov_b32_e32 v173, v142
	v_mov_b32_e32 v134, v131
	v_mov_b32_e32 v142, v139
	s_waitcnt lgkmcnt(3)
	v_pk_mul_f32 v[64:65], v[104:105], v[154:155] op_sel_hi:[1,0]
	v_pk_mul_f32 v[66:67], v[144:145], v[154:155] op_sel_hi:[1,0]
	global_load_dword v124, v[106:107], off
	v_pk_mul_f32 v[68:69], v[146:147], v[154:155] op_sel_hi:[1,0]
	global_load_dwordx4 v[48:51], v[48:49], off
	v_pk_mul_f32 v[70:71], v[148:149], v[154:155] op_sel_hi:[1,0]
	s_waitcnt lgkmcnt(2)
	v_pk_mul_f32 v[128:129], v[56:57], v[114:115] op_sel_hi:[1,0]
	v_pk_mul_f32 v[130:131], v[60:61], v[114:115] op_sel_hi:[1,0]
	v_pk_mul_f32 v[136:137], v[132:133], v[114:115] op_sel_hi:[1,0]
	v_pk_mul_f32 v[138:139], v[140:141], v[114:115] op_sel_hi:[1,0]
	s_waitcnt lgkmcnt(1)
	v_pk_mul_f32 v[144:145], v[150:151], v[112:113] op_sel_hi:[1,0]
	v_pk_mul_f32 v[146:147], v[156:157], v[112:113] op_sel_hi:[1,0]
	v_pk_mul_f32 v[148:149], v[158:159], v[112:113] op_sel_hi:[1,0]
	v_pk_mul_f32 v[150:151], v[172:173], v[112:113] op_sel_hi:[1,0]
	s_waitcnt lgkmcnt(0)
	v_pk_mul_f32 v[56:57], v[58:59], v[88:89] op_sel_hi:[1,0]
	v_pk_mul_f32 v[58:59], v[62:63], v[88:89] op_sel_hi:[1,0]
	v_pk_mul_f32 v[60:61], v[134:135], v[88:89] op_sel_hi:[1,0]
	v_pk_mul_f32 v[62:63], v[142:143], v[88:89] op_sel_hi:[1,0]
	ds_write_b128 v120, v[64:67]
	ds_write_b128 v120, v[68:71] offset:16
	ds_write_b128 v120, v[128:131] offset:528
	ds_write_b128 v120, v[136:139] offset:544
	ds_write_b128 v120, v[144:147] offset:1056
	ds_write_b128 v120, v[148:151] offset:1072
	ds_write_b128 v120, v[56:59] offset:1584
	ds_write_b128 v120, v[60:63] offset:1600
	v_add_u32_e32 v123, s48, v87
	s_waitcnt lgkmcnt(0)
	v_add_u32_e32 v125, 0x800, v123
	v_add_u32_e32 v126, 0x1000, v123
	v_add_u32_e32 v127, 0x1800, v123
	ds_read2_b64 v[56:59], v123 offset1:66
	ds_read2_b64 v[60:63], v123 offset0:132 offset1:198
	ds_read2_b64 v[64:67], v125 offset0:8 offset1:74
	ds_read2_b64 v[68:71], v125 offset0:140 offset1:206
	ds_read2_b64 v[128:131], v126 offset0:16 offset1:82
	ds_read2_b64 v[132:135], v126 offset0:148 offset1:214
	ds_read2_b64 v[136:139], v127 offset0:24 offset1:90
	ds_read2_b64 v[140:143], v127 offset0:156 offset1:222
	s_waitcnt lgkmcnt(7)
	v_add_f32_e32 v56, v152, v56
	v_mfma_f32_16x16x32_bf16 v[72:75], v[72:75], v[0:3], 0
	v_add_f32_e32 v57, v153, v57
	v_lshl_add_u64 v[106:107], v[106:107], 0, 64
	v_cvt_pk_bf16_f32 v146, v56, v57
	ds_write_b32 v208, v146
	v_fma_f32 v144, -v103, v57, v58
	v_fma_f32 v145, v103, v56, v59
	v_fma_f32 v58, v102, v56, v144
	v_fma_f32 v59, v102, v57, v145
	v_cvt_pk_bf16_f32 v147, v58, v59
	ds_write_b32 v208, v147 offset:272
	s_waitcnt lgkmcnt(8)
	v_fma_f32 v144, -v103, v59, v60
	v_fma_f32 v145, v103, v58, v61
	v_fma_f32 v60, v102, v58, v144
	v_fma_f32 v61, v102, v59, v145
	v_cvt_pk_bf16_f32 v146, v60, v61
	ds_write_b32 v208, v146 offset:544
	v_fma_f32 v144, -v103, v61, v62
	v_fma_f32 v145, v103, v60, v63
	v_fma_f32 v62, v102, v60, v144
	v_fma_f32 v63, v102, v61, v145
	v_cvt_pk_bf16_f32 v147, v62, v63
	ds_write_b32 v208, v147 offset:816
	s_waitcnt lgkmcnt(9)
	v_fma_f32 v144, -v103, v63, v64
	v_fma_f32 v145, v103, v62, v65
	v_fma_f32 v64, v102, v62, v144
	v_fma_f32 v65, v102, v63, v145
	v_cvt_pk_bf16_f32 v146, v64, v65
	ds_write_b32 v208, v146 offset:1088
	v_fma_f32 v144, -v103, v65, v66
	v_fma_f32 v145, v103, v64, v67
	v_fma_f32 v66, v102, v64, v144
	v_fma_f32 v67, v102, v65, v145
	v_cvt_pk_bf16_f32 v147, v66, v67
	ds_write_b32 v208, v147 offset:1360
	s_waitcnt lgkmcnt(10)
	v_fma_f32 v144, -v103, v67, v68
	v_fma_f32 v145, v103, v66, v69
	v_fma_f32 v68, v102, v66, v144
	v_fma_f32 v69, v102, v67, v145
	v_cvt_pk_bf16_f32 v146, v68, v69
	ds_write_b32 v208, v146 offset:1632
	v_fma_f32 v144, -v103, v69, v70
	v_fma_f32 v145, v103, v68, v71
	v_fma_f32 v70, v102, v68, v144
	v_fma_f32 v71, v102, v69, v145
	v_cvt_pk_bf16_f32 v147, v70, v71
	ds_write_b32 v208, v147 offset:1904
	s_waitcnt lgkmcnt(11)
; __device__ __forceinline__ float rs_of(float ss) { return __builtin_amdgcn_rsqf(ss * (1.0f / 2048.0f) + 1e-6f); }
; __device__ __forceinline__ void s5_task(const Args& a, const bf16_t* XN, const float* SS, bf16_t* Y, LAS float* S, int b, int g, int lane) {
;     ...
;         const u32x4 uraw = unext; const float rsl = rs_of(ssn);
;         { const size_t rn = (blk + 1 < SEQ / 16) ? row0 + 16 : row0;
;           unext = *(const u32x4*)(XN + (rn + n16) * DM + 16 * g + 8 * (j4 & 1)); ssn = SS[rn + n16]; }
;         float rsw[4];
; #pragma unroll
;         for (int i = 0; i < 4; ++i) rsw[i] = __shfl(rsl, 4 * j4 + i);
;         const bf16x8 ua = __builtin_bit_cast(bf16x8, uraw);
;         f32x4 bu[8];
; #pragma unroll
;         for (int ct = 0; ct < 8; ++ct) bu[ct] = MFMA16(ua, bw[ct], ((f32x4){0.f, 0.f, 0.f, 0.f}));
;         const f32x4 yd = MFMA16(ua, dw, ((f32x4){0.f, 0.f, 0.f, 0.f}));
; #pragma unroll
;         for (int i = 0; i < 4; ++i) { LAS float* w = S + (4 * j4 + i) * 132 + 8 * n16; const float q = rsw[i];
;             *(LAS f32x4*)w = (f32x4){bu[0][i] * q, bu[1][i] * q, bu[2][i] * q, bu[3][i] * q}; *(LAS f32x4*)(w + 4) = (f32x4){bu[4][i] * q, bu[5][i] * q, bu[6][i] * q, bu[7][i] * q}; }
;     ...
;         for (int tt = 0; tt < 16; ++tt) { LAS f32x2* sp = (LAS f32x2*)(S + tt * 132 + 2 * lane); const f32x2 v = *sp;
;             const float nre = ar * sre - ai * sim + v.x, nim = ar * sim + ai * sre + v.y; sre = nre; sim = nim; *sp = (f32x2){sre, sim}; }
;         LDS_WAIT();
;         f32x4 y = {0.f, 0.f, 0.f, 0.f};
; #pragma unroll
;         for (int kk = 0; kk < 4; ++kk) { const f32x4 s0 = *(LAS f32x4*)(S + n16 * 132 + 32 * kk + 8 * j4), s1 = *(LAS f32x4*)(S + n16 * 132 + 32 * kk + 8 * j4 + 4);
;             const bf16x8 sa = __builtin_bit_cast(bf16x8, (u32x4){cvtpk(s0[0], s0[1]), cvtpk(s0[2], s0[3]), cvtpk(s1[0], s1[1]), cvtpk(s1[2], s1[3])});
;             y = MFMA16(sa, cw[kk], y); }
; #pragma unroll
;         for (int i = 0; i < 4; ++i) { const float v = y[i] + yd[i] * rsw[i];
;             const float ge = v * sigmoid_f(1.5957691216057308f * (v + 0.044715f * v * v * v));
;             YS[(4 * j4 + i) * 16 + n16] = (unsigned short)(cvtpk(ge, 0.f) & 0xffffu); }
;         LDS_WAIT();
;         { const u32x2 o = *(LAS u32x2*)(YS + 4 * lane);
;           *(u32x2*)(Y + (row0 + (lane >> 2)) * DM + 16 * g + 4 * (lane & 3)) = o; }
;         LDS_WAIT();
	v_fma_f32 v144, -v103, v71, v128
	v_fma_f32 v145, v103, v70, v129
	v_fma_f32 v128, v102, v70, v144
	v_fma_f32 v129, v102, v71, v145
	v_cvt_pk_bf16_f32 v146, v128, v129
	ds_write_b32 v208, v146 offset:2176
	v_fma_f32 v144, -v103, v129, v130
	v_fma_f32 v145, v103, v128, v131
	v_fma_f32 v130, v102, v128, v144
	v_fma_f32 v131, v102, v129, v145
	v_cvt_pk_bf16_f32 v147, v130, v131
	ds_write_b32 v208, v147 offset:2448
	s_waitcnt lgkmcnt(12)
	v_fma_f32 v144, -v103, v131, v132
	v_fma_f32 v145, v103, v130, v133
	v_fma_f32 v132, v102, v130, v144
	v_fma_f32 v133, v102, v131, v145
	v_cvt_pk_bf16_f32 v146, v132, v133
	ds_write_b32 v208, v146 offset:2720
	v_fma_f32 v144, -v103, v133, v134
	v_fma_f32 v145, v103, v132, v135
	v_fma_f32 v134, v102, v132, v144
	v_fma_f32 v135, v102, v133, v145
	v_cvt_pk_bf16_f32 v147, v134, v135
	ds_write_b32 v208, v147 offset:2992
	s_waitcnt lgkmcnt(13)
	v_fma_f32 v144, -v103, v135, v136
	v_fma_f32 v145, v103, v134, v137
	v_fma_f32 v136, v102, v134, v144
	v_fma_f32 v137, v102, v135, v145
	v_cvt_pk_bf16_f32 v146, v136, v137
	ds_write_b32 v208, v146 offset:3264
	v_fma_f32 v144, -v103, v137, v138
	v_fma_f32 v145, v103, v136, v139
	v_fma_f32 v138, v102, v136, v144
	v_fma_f32 v139, v102, v137, v145
	v_cvt_pk_bf16_f32 v147, v138, v139
	ds_write_b32 v208, v147 offset:3536
	s_waitcnt lgkmcnt(14)
	v_fma_f32 v144, -v103, v139, v140
	v_fma_f32 v145, v103, v138, v141
	v_fma_f32 v140, v102, v138, v144
	v_fma_f32 v141, v102, v139, v145
	v_cvt_pk_bf16_f32 v146, v140, v141
	ds_write_b32 v208, v146 offset:3808
	v_fma_f32 v144, -v103, v141, v142
	v_fma_f32 v145, v103, v140, v143
	v_fma_f32 v104, v102, v140, v144
	v_fma_f32 v105, v102, v141, v145
	v_cvt_pk_bf16_f32 v147, v104, v105
	ds_write_b32 v208, v147 offset:4080
	s_waitcnt lgkmcnt(0)
	ds_read_b128 v[56:59], v207
	ds_read_b128 v[60:63], v207 offset:64
	ds_read_b128 v[64:67], v207 offset:128
	ds_read_b128 v[68:71], v207 offset:192
	s_waitcnt lgkmcnt(3)
	v_mfma_f32_16x16x32_bf16 v[56:59], v[56:59], v[36:39], 0
	s_waitcnt lgkmcnt(2)
	v_mfma_f32_16x16x32_bf16 v[56:59], v[60:63], v[32:35], v[56:59]
	s_waitcnt lgkmcnt(1)
	v_mfma_f32_16x16x32_bf16 v[56:59], v[64:67], v[28:31], v[56:59]
	s_waitcnt lgkmcnt(0)
	v_mfma_f32_16x16x32_bf16 v[56:59], v[68:71], v[24:27], v[56:59]
	s_nop 7
	v_fma_f32 v56, v72, v154, v56
	v_fma_f32 v57, v73, v114, v57
	v_fma_f32 v58, v74, v112, v58
	v_fmac_f32_e32 v59, v75, v88
	v_mul_f32_e32 v60, 0x3d372713, v56
	v_mul_f32_e32 v61, 0x3d372713, v57
	v_mul_f32_e32 v62, 0x3d372713, v58
	v_mul_f32_e32 v63, 0x3d372713, v59
	v_mul_f32_e32 v60, v56, v60
	v_mul_f32_e32 v61, v57, v61
	v_mul_f32_e32 v62, v58, v62
	v_mul_f32_e32 v63, v59, v63
	v_fma_f32 v60, v56, v60, v56
	v_fma_f32 v61, v57, v61, v57
	v_fma_f32 v62, v58, v62, v58
	v_fma_f32 v63, v59, v63, v59
	v_mul_f32_e32 v60, 0x3fcc422a, v60
	v_mul_f32_e32 v61, 0x3fcc422a, v61
	v_mul_f32_e32 v62, 0x3fcc422a, v62
	v_mul_f32_e32 v63, 0x3fcc422a, v63
	v_mul_f32_e32 v60, 0xbfb8aa3b, v60
	v_mul_f32_e32 v61, 0xbfb8aa3b, v61
	v_mul_f32_e32 v62, 0xbfb8aa3b, v62
	v_mul_f32_e32 v63, 0xbfb8aa3b, v63
	v_exp_f32_e32 v60, v60
	v_exp_f32_e32 v61, v61
	v_exp_f32_e32 v62, v62
	v_exp_f32_e32 v63, v63
	v_add_f32_e32 v60, 1.0, v60
	v_add_f32_e32 v61, 1.0, v61
	v_add_f32_e32 v62, 1.0, v62
	v_add_f32_e32 v63, 1.0, v63
	v_rcp_f32_e32 v60, v60
	v_rcp_f32_e32 v61, v61
	v_rcp_f32_e32 v62, v62
	v_rcp_f32_e32 v63, v63
	v_mul_f32_e32 v56, v56, v60
	v_mul_f32_e32 v57, v57, v61
	v_mul_f32_e32 v58, v58, v62
	v_mul_f32_e32 v59, v59, v63
	v_cvt_pk_bf16_f32 v56, v56, s0
	v_cvt_pk_bf16_f32 v57, v57, s0
	v_cvt_pk_bf16_f32 v58, v58, s0
	v_cvt_pk_bf16_f32 v59, v59, s0
	ds_write_b16 v122, v56 offset:8448
	ds_write_b16 v122, v57 offset:8480
	ds_write_b16 v122, v58 offset:8512
	ds_write_b16 v122, v59 offset:8544
	s_waitcnt lgkmcnt(0)
	ds_read_b64 v[56:57], v123 offset:8448
	v_lshl_add_u64 v[58:59], v[110:111], 0, s[28:29]
	s_add_u32 s28, s28, 0x10000
	s_addc_u32 s29, s29, 0
	s_cmp_lg_u32 s28, 0x7f0000
	s_waitcnt lgkmcnt(0)
	global_store_dwordx2 v[58:59], v[56:57], off
	s_waitcnt lgkmcnt(0)
	s_cbranch_scc1 .LBB0_666
	s_waitcnt vmcnt(1)
	v_mfma_f32_16x16x32_bf16 v[56:59], v[48:51], v[4:7], 0
	v_fmamk_f32 v4, v124, 0x3a000000, v119
	v_rsq_f32_e32 v4, v4
	s_lshl_b32 s38, s57, 1
	v_mfma_f32_16x16x32_bf16 v[60:63], v[48:51], v[8:11], 0
	s_add_i32 s56, s56, s50
	ds_bpermute_b32 v10, v113, v4
	ds_bpermute_b32 v8, v115, v4
	v_mfma_f32_16x16x32_bf16 v[12:15], v[48:51], v[12:15], 0
	v_mov_b32_e32 v64, v56
	s_nop 2
	v_mov_b32_e32 v65, v60
	ds_bpermute_b32 v6, v116, v4
	v_mfma_f32_16x16x32_bf16 v[16:19], v[48:51], v[16:19], 0
	s_waitcnt lgkmcnt(2)
	v_pk_mul_f32 v[64:65], v[64:65], v[10:11] op_sel_hi:[1,0]
	v_mov_b32_e32 v66, v12
	v_mov_b32_e32 v60, v57
	v_mfma_f32_16x16x32_bf16 v[20:23], v[48:51], v[20:23], 0
	ds_bpermute_b32 v4, v117, v4
	s_nop 1
	v_mov_b32_e32 v67, v16
	v_pk_mul_f32 v[66:67], v[66:67], v[10:11] op_sel_hi:[1,0]
	v_mfma_f32_16x16x32_bf16 v[40:43], v[48:51], v[40:43], 0
	ds_write_b128 v120, v[64:67]
	s_nop 0
	v_mov_b32_e32 v64, v20
	v_mov_b32_e32 v16, v13
	v_mfma_f32_16x16x32_bf16 v[44:47], v[48:51], v[44:47], 0
	v_mov_b32_e32 v12, v58
	s_nop 1
	v_mov_b32_e32 v65, v40
	v_pk_mul_f32 v[64:65], v[64:65], v[10:11] op_sel_hi:[1,0]
	v_mfma_f32_16x16x32_bf16 v[52:55], v[48:51], v[52:55], 0
	v_mov_b32_e32 v40, v21
	s_nop 0
	v_mov_b32_e32 v66, v44
	v_mov_b32_e32 v13, v62
	v_mov_b32_e32 v62, v59
	v_mfma_f32_16x16x32_bf16 v[0:3], v[48:51], v[0:3], 0
	s_nop 1
	v_mov_b32_e32 v67, v52
	v_pk_mul_f32 v[66:67], v[66:67], v[10:11] op_sel_hi:[1,0]
	ds_write_b128 v120, v[64:67] offset:16
	s_waitcnt lgkmcnt(4)
; #define LAS __attribute__((address_space(3)))
; #define LDS_WAIT() asm volatile("s_waitcnt lgkmcnt(0)" ::: "memory")
; __device__ __forceinline__ void s5_task(const Args& a, const bf16_t* XN, const float* SS, bf16_t* Y, LAS float* S, int b, int g, int lane) {
;     ...
;         for (int i = 0; i < 4; ++i) { LAS float* w = S + (4 * j4 + i) * 132 + 8 * n16; const float q = rsw[i];
;             *(LAS f32x4*)w = (f32x4){bu[0][i] * q, bu[1][i] * q, bu[2][i] * q, bu[3][i] * q}; *(LAS f32x4*)(w + 4) = (f32x4){bu[4][i] * q, bu[5][i] * q, bu[6][i] * q, bu[7][i] * q}; }
;         LDS_WAIT();
; #pragma unroll
;         for (int tt = 0; tt < 16; ++tt) { LAS f32x2* sp = (LAS f32x2*)(S + tt * 132 + 2 * lane); const f32x2 v = *sp;
;             const float nre = ar * sre - ai * sim + v.x, nim = ar * sim + ai * sre + v.y; sre = nre; sim = nim; *sp = (f32x2){sre, sim}; }
	v_pk_mul_f32 v[64:65], v[60:61], v[8:9] op_sel_hi:[1,0]
	v_pk_mul_f32 v[66:67], v[16:17], v[8:9] op_sel_hi:[1,0]
	v_mov_b32_e32 v52, v45
	ds_write_b128 v120, v[64:67] offset:528
	v_pk_mul_f32 v[64:65], v[40:41], v[8:9] op_sel_hi:[1,0]
	v_pk_mul_f32 v[66:67], v[52:53], v[8:9] op_sel_hi:[1,0]
	ds_write_b128 v120, v[64:67] offset:544
	s_waitcnt lgkmcnt(5)
	v_pk_mul_f32 v[64:65], v[12:13], v[6:7] op_sel_hi:[1,0]
	v_mov_b32_e32 v12, v14
	v_mov_b32_e32 v13, v18
	v_pk_mul_f32 v[66:67], v[12:13], v[6:7] op_sel_hi:[1,0]
	v_mov_b32_e32 v12, v22
	v_mov_b32_e32 v13, v42
	ds_write_b128 v120, v[64:67] offset:1056
	v_pk_mul_f32 v[64:65], v[12:13], v[6:7] op_sel_hi:[1,0]
	v_mov_b32_e32 v12, v46
	v_mov_b32_e32 v13, v54
	v_mov_b32_e32 v18, v15
	v_pk_mul_f32 v[66:67], v[12:13], v[6:7] op_sel_hi:[1,0]
	s_waitcnt lgkmcnt(5)
	v_pk_mul_f32 v[12:13], v[62:63], v[4:5] op_sel_hi:[1,0]
	v_pk_mul_f32 v[14:15], v[18:19], v[4:5] op_sel_hi:[1,0]
	v_mov_b32_e32 v42, v23
	v_mov_b32_e32 v54, v47
	ds_write_b128 v120, v[12:15] offset:1584
	v_pk_mul_f32 v[12:13], v[42:43], v[4:5] op_sel_hi:[1,0]
	v_pk_mul_f32 v[14:15], v[54:55], v[4:5] op_sel_hi:[1,0]
	ds_write_b128 v120, v[64:67] offset:1072
	ds_write_b128 v120, v[12:15] offset:1600
	s_waitcnt lgkmcnt(0)
	ds_read2_b64 v[12:15], v123 offset1:66
	v_pk_mul_f32 v[16:17], v[80:81], v[104:105] op_sel:[0,1]
	s_add_i32 s43, s43, s49
	v_pk_fma_f32 v[18:19], v[102:103], v[104:105], v[16:17] neg_lo:[0,0,1] neg_hi:[0,0,1]
	v_pk_fma_f32 v[16:17], v[102:103], v[104:105], v[16:17] op_sel_hi:[1,0,1]
	s_cmp_ge_i32 s56, s34
	v_mov_b32_e32 v19, v17
	s_waitcnt lgkmcnt(0)
	v_pk_add_f32 v[12:13], v[18:19], v[12:13]
	s_nop 0
	v_pk_mul_f32 v[16:17], v[78:79], v[12:13]
	s_nop 0
	v_pk_fma_f32 v[18:19], v[76:77], v[12:13], v[16:17] op_sel:[0,0,1] op_sel_hi:[1,1,0] neg_lo:[0,0,1] neg_hi:[0,0,1]
	v_pk_fma_f32 v[16:17], v[76:77], v[12:13], v[16:17] op_sel:[0,0,1] op_sel_hi:[1,1,0]
	s_nop 0
	v_mov_b32_e32 v19, v17
	v_pk_add_f32 v[16:17], v[14:15], v[18:19]
	ds_write2_b64 v123, v[12:13], v[16:17] offset1:66
	ds_read2_b64 v[12:15], v123 offset0:132 offset1:198
	v_pk_mul_f32 v[18:19], v[78:79], v[16:17]
	s_nop 0
	v_pk_fma_f32 v[20:21], v[76:77], v[16:17], v[18:19] op_sel:[0,0,1] op_sel_hi:[1,1,0] neg_lo:[0,0,1] neg_hi:[0,0,1]
	v_pk_fma_f32 v[16:17], v[76:77], v[16:17], v[18:19] op_sel:[0,0,1] op_sel_hi:[1,1,0]
	s_nop 0
	v_mov_b32_e32 v21, v17
	s_waitcnt lgkmcnt(0)
	v_pk_add_f32 v[12:13], v[12:13], v[20:21]
	s_nop 0
	v_pk_mul_f32 v[16:17], v[78:79], v[12:13]
	s_nop 0
	v_pk_fma_f32 v[18:19], v[76:77], v[12:13], v[16:17] op_sel:[0,0,1] op_sel_hi:[1,1,0] neg_lo:[0,0,1] neg_hi:[0,0,1]
	v_pk_fma_f32 v[16:17], v[76:77], v[12:13], v[16:17] op_sel:[0,0,1] op_sel_hi:[1,1,0]
	s_nop 0
	v_mov_b32_e32 v19, v17
	v_pk_add_f32 v[16:17], v[14:15], v[18:19]
	ds_write2_b64 v123, v[12:13], v[16:17] offset0:132 offset1:198
	ds_read2_b64 v[12:15], v125 offset0:8 offset1:74
	v_pk_mul_f32 v[18:19], v[78:79], v[16:17]
	s_nop 0
	v_pk_fma_f32 v[20:21], v[76:77], v[16:17], v[18:19] op_sel:[0,0,1] op_sel_hi:[1,1,0] neg_lo:[0,0,1] neg_hi:[0,0,1]
	v_pk_fma_f32 v[16:17], v[76:77], v[16:17], v[18:19] op_sel:[0,0,1] op_sel_hi:[1,1,0]
	s_nop 0
	v_mov_b32_e32 v21, v17
	s_waitcnt lgkmcnt(0)
	v_pk_add_f32 v[12:13], v[12:13], v[20:21]
	s_nop 0
	v_pk_mul_f32 v[16:17], v[78:79], v[12:13]
	s_nop 0
	v_pk_fma_f32 v[18:19], v[76:77], v[12:13], v[16:17] op_sel:[0,0,1] op_sel_hi:[1,1,0] neg_lo:[0,0,1] neg_hi:[0,0,1]
	v_pk_fma_f32 v[16:17], v[76:77], v[12:13], v[16:17] op_sel:[0,0,1] op_sel_hi:[1,1,0]
	s_nop 0
	v_mov_b32_e32 v19, v17
	v_pk_add_f32 v[16:17], v[14:15], v[18:19]
	ds_write2_b64 v125, v[12:13], v[16:17] offset0:8 offset1:74
	ds_read2_b64 v[12:15], v125 offset0:140 offset1:206
	v_pk_mul_f32 v[18:19], v[78:79], v[16:17]
	s_nop 0
	v_pk_fma_f32 v[20:21], v[76:77], v[16:17], v[18:19] op_sel:[0,0,1] op_sel_hi:[1,1,0] neg_lo:[0,0,1] neg_hi:[0,0,1]
	v_pk_fma_f32 v[16:17], v[76:77], v[16:17], v[18:19] op_sel:[0,0,1] op_sel_hi:[1,1,0]
	s_nop 0
	v_mov_b32_e32 v21, v17
	s_waitcnt lgkmcnt(0)
	v_pk_add_f32 v[12:13], v[12:13], v[20:21]
	s_nop 0
	v_pk_mul_f32 v[16:17], v[78:79], v[12:13]
	s_nop 0
	v_pk_fma_f32 v[18:19], v[76:77], v[12:13], v[16:17] op_sel:[0,0,1] op_sel_hi:[1,1,0] neg_lo:[0,0,1] neg_hi:[0,0,1]
	v_pk_fma_f32 v[16:17], v[76:77], v[12:13], v[16:17] op_sel:[0,0,1] op_sel_hi:[1,1,0]
	s_nop 0
	v_mov_b32_e32 v19, v17
	v_pk_add_f32 v[16:17], v[14:15], v[18:19]
	ds_write2_b64 v125, v[12:13], v[16:17] offset0:140 offset1:206
	ds_read2_b64 v[12:15], v126 offset0:16 offset1:82
	v_pk_mul_f32 v[18:19], v[78:79], v[16:17]
	s_nop 0
	v_pk_fma_f32 v[20:21], v[76:77], v[16:17], v[18:19] op_sel:[0,0,1] op_sel_hi:[1,1,0] neg_lo:[0,0,1] neg_hi:[0,0,1]
	v_pk_fma_f32 v[16:17], v[76:77], v[16:17], v[18:19] op_sel:[0,0,1] op_sel_hi:[1,1,0]
	s_nop 0
	v_mov_b32_e32 v21, v17
	s_waitcnt lgkmcnt(0)
	v_pk_add_f32 v[12:13], v[12:13], v[20:21]
	s_nop 0
	v_pk_mul_f32 v[16:17], v[78:79], v[12:13]
	s_nop 0
	v_pk_fma_f32 v[18:19], v[76:77], v[12:13], v[16:17] op_sel:[0,0,1] op_sel_hi:[1,1,0] neg_lo:[0,0,1] neg_hi:[0,0,1]
	v_pk_fma_f32 v[16:17], v[76:77], v[12:13], v[16:17] op_sel:[0,0,1] op_sel_hi:[1,1,0]
	s_nop 0
	v_mov_b32_e32 v19, v17
	v_pk_add_f32 v[16:17], v[14:15], v[18:19]
	ds_write2_b64 v126, v[12:13], v[16:17] offset0:16 offset1:82
	ds_read2_b64 v[12:15], v126 offset0:148 offset1:214
	v_pk_mul_f32 v[18:19], v[78:79], v[16:17]
	s_nop 0
	v_pk_fma_f32 v[20:21], v[76:77], v[16:17], v[18:19] op_sel:[0,0,1] op_sel_hi:[1,1,0] neg_lo:[0,0,1] neg_hi:[0,0,1]
	v_pk_fma_f32 v[16:17], v[76:77], v[16:17], v[18:19] op_sel:[0,0,1] op_sel_hi:[1,1,0]
	s_nop 0
	v_mov_b32_e32 v21, v17
	s_waitcnt lgkmcnt(0)
; __device__ __forceinline__ unsigned cvtpk(float lo, float hi) { f32x2_t v = {lo, hi}; bf16x2_t b = __builtin_convertvector(v, bf16x2_t); return __builtin_bit_cast(unsigned, b); }
; __device__ __forceinline__ float sigmoid_f(float x) { return __builtin_amdgcn_rcpf(1.0f + __builtin_amdgcn_exp2f(-1.4426950408889634f * x)); }
; #define LAS __attribute__((address_space(3)))
; #define LDS_WAIT() asm volatile("s_waitcnt lgkmcnt(0)" ::: "memory")
; #define MFMA16(a, b, c) __builtin_amdgcn_mfma_f32_16x16x32_bf16((a), (b), (c), 0, 0, 0)
; __device__ __forceinline__ void s5_task(const Args& a, const bf16_t* XN, const float* SS, bf16_t* Y, LAS float* S, int b, int g, int lane) {
;     ...
;         for (int tt = 0; tt < 16; ++tt) { LAS f32x2* sp = (LAS f32x2*)(S + tt * 132 + 2 * lane); const f32x2 v = *sp;
;             const float nre = ar * sre - ai * sim + v.x, nim = ar * sim + ai * sre + v.y; sre = nre; sim = nim; *sp = (f32x2){sre, sim}; }
;         LDS_WAIT();
;         f32x4 y = {0.f, 0.f, 0.f, 0.f};
; #pragma unroll
;         for (int kk = 0; kk < 4; ++kk) { const f32x4 s0 = *(LAS f32x4*)(S + n16 * 132 + 32 * kk + 8 * j4), s1 = *(LAS f32x4*)(S + n16 * 132 + 32 * kk + 8 * j4 + 4);
;             const bf16x8 sa = __builtin_bit_cast(bf16x8, (u32x4){cvtpk(s0[0], s0[1]), cvtpk(s0[2], s0[3]), cvtpk(s1[0], s1[1]), cvtpk(s1[2], s1[3])});
;             y = MFMA16(sa, cw[kk], y); }
; #pragma unroll
;         for (int i = 0; i < 4; ++i) { const float v = y[i] + yd[i] * rsw[i];
;             const float ge = v * sigmoid_f(1.5957691216057308f * (v + 0.044715f * v * v * v));
;             YS[(4 * j4 + i) * 16 + n16] = (unsigned short)(cvtpk(ge, 0.f) & 0xffffu); }
;         LDS_WAIT();
;         { const u32x2 o = *(LAS u32x2*)(YS + 4 * lane);
;           *(u32x2*)(Y + (row0 + (lane >> 2)) * DM + 16 * g + 4 * (lane & 3)) = o; }
	v_pk_add_f32 v[12:13], v[12:13], v[20:21]
	s_nop 0
	v_pk_mul_f32 v[16:17], v[78:79], v[12:13]
	s_nop 0
	v_pk_fma_f32 v[18:19], v[76:77], v[12:13], v[16:17] op_sel:[0,0,1] op_sel_hi:[1,1,0] neg_lo:[0,0,1] neg_hi:[0,0,1]
	v_pk_fma_f32 v[16:17], v[76:77], v[12:13], v[16:17] op_sel:[0,0,1] op_sel_hi:[1,1,0]
	s_nop 0
	v_mov_b32_e32 v19, v17
	v_pk_add_f32 v[16:17], v[14:15], v[18:19]
	ds_write2_b64 v126, v[12:13], v[16:17] offset0:148 offset1:214
	ds_read2_b64 v[12:15], v127 offset0:24 offset1:90
	v_pk_mul_f32 v[18:19], v[78:79], v[16:17]
	s_nop 0
	v_pk_fma_f32 v[20:21], v[76:77], v[16:17], v[18:19] op_sel:[0,0,1] op_sel_hi:[1,1,0] neg_lo:[0,0,1] neg_hi:[0,0,1]
	v_pk_fma_f32 v[16:17], v[76:77], v[16:17], v[18:19] op_sel:[0,0,1] op_sel_hi:[1,1,0]
	s_nop 0
	v_mov_b32_e32 v21, v17
	s_waitcnt lgkmcnt(0)
	v_pk_add_f32 v[12:13], v[12:13], v[20:21]
	s_nop 0
	v_pk_mul_f32 v[16:17], v[78:79], v[12:13]
	s_nop 0
	v_pk_fma_f32 v[18:19], v[76:77], v[12:13], v[16:17] op_sel:[0,0,1] op_sel_hi:[1,1,0] neg_lo:[0,0,1] neg_hi:[0,0,1]
	v_pk_fma_f32 v[16:17], v[76:77], v[12:13], v[16:17] op_sel:[0,0,1] op_sel_hi:[1,1,0]
	s_nop 0
	v_mov_b32_e32 v19, v17
	v_pk_add_f32 v[16:17], v[14:15], v[18:19]
	ds_write2_b64 v127, v[12:13], v[16:17] offset0:24 offset1:90
	ds_read2_b64 v[12:15], v127 offset0:156 offset1:222
	v_pk_mul_f32 v[18:19], v[78:79], v[16:17]
	s_nop 0
	v_pk_fma_f32 v[20:21], v[76:77], v[16:17], v[18:19] op_sel:[0,0,1] op_sel_hi:[1,1,0] neg_lo:[0,0,1] neg_hi:[0,0,1]
	v_pk_fma_f32 v[16:17], v[76:77], v[16:17], v[18:19] op_sel:[0,0,1] op_sel_hi:[1,1,0]
	s_nop 0
	v_mov_b32_e32 v21, v17
	s_waitcnt lgkmcnt(0)
	v_pk_add_f32 v[12:13], v[12:13], v[20:21]
	s_nop 0
	v_pk_mul_f32 v[16:17], v[78:79], v[12:13]
	s_nop 0
	v_pk_fma_f32 v[18:19], v[76:77], v[12:13], v[16:17] op_sel:[0,0,1] op_sel_hi:[1,1,0] neg_lo:[0,0,1] neg_hi:[0,0,1]
	v_pk_fma_f32 v[16:17], v[76:77], v[12:13], v[16:17] op_sel:[0,0,1] op_sel_hi:[1,1,0]
	s_nop 0
	v_mov_b32_e32 v19, v17
	v_pk_add_f32 v[14:15], v[14:15], v[18:19]
	ds_write2_b64 v127, v[12:13], v[14:15] offset0:156 offset1:222
	s_waitcnt lgkmcnt(0)
	ds_read_b128 v[12:15], v121
	ds_read_b128 v[16:19], v121 offset:16
	s_waitcnt lgkmcnt(1)
	v_cvt_pk_bf16_f32 v12, v12, v13
	v_cvt_pk_bf16_f32 v13, v14, v15
	s_waitcnt lgkmcnt(0)
	v_cvt_pk_bf16_f32 v14, v16, v17
	v_cvt_pk_bf16_f32 v15, v18, v19
	ds_read_b128 v[16:19], v121 offset:128
	ds_read_b128 v[20:23], v121 offset:144
	v_mfma_f32_16x16x32_bf16 v[12:15], v[12:15], v[36:39], 0
	s_waitcnt lgkmcnt(1)
	v_cvt_pk_bf16_f32 v16, v16, v17
	v_cvt_pk_bf16_f32 v17, v18, v19
	s_waitcnt lgkmcnt(0)
	v_cvt_pk_bf16_f32 v18, v20, v21
	v_cvt_pk_bf16_f32 v19, v22, v23
	ds_read_b128 v[20:23], v121 offset:256
	ds_read_b128 v[36:39], v121 offset:272
	v_mfma_f32_16x16x32_bf16 v[12:15], v[16:19], v[32:35], v[12:15]
	s_waitcnt lgkmcnt(1)
	v_cvt_pk_bf16_f32 v16, v20, v21
	v_cvt_pk_bf16_f32 v17, v22, v23
	s_waitcnt lgkmcnt(0)
	v_cvt_pk_bf16_f32 v18, v36, v37
	v_cvt_pk_bf16_f32 v19, v38, v39
	ds_read_b128 v[20:23], v121 offset:384
	ds_read_b128 v[32:35], v121 offset:400
	v_mfma_f32_16x16x32_bf16 v[12:15], v[16:19], v[28:31], v[12:15]
	s_waitcnt lgkmcnt(1)
	v_cvt_pk_bf16_f32 v16, v20, v21
	v_cvt_pk_bf16_f32 v17, v22, v23
	s_waitcnt lgkmcnt(0)
	v_cvt_pk_bf16_f32 v18, v32, v33
	v_cvt_pk_bf16_f32 v19, v34, v35
	s_nop 1
	v_mfma_f32_16x16x32_bf16 v[12:15], v[16:19], v[24:27], v[12:15]
	s_nop 7
	v_fma_f32 v0, v0, v10, v12
	v_mul_f32_e32 v5, 0x3d372713, v0
	v_mul_f32_e32 v5, v0, v5
	v_fma_f32 v1, v1, v8, v13
	v_fma_f32 v5, v0, v5, v0
	v_mul_f32_e32 v7, 0x3d372713, v1
	v_mul_f32_e32 v5, 0x3fcc422a, v5
	v_mul_f32_e32 v7, v1, v7
	v_mul_f32_e32 v5, 0xbfb8aa3b, v5
	v_fma_f32 v7, v1, v7, v1
	v_exp_f32_e32 v5, v5
	v_mul_f32_e32 v7, 0x3fcc422a, v7
	v_mul_f32_e32 v7, 0xbfb8aa3b, v7
	v_exp_f32_e32 v7, v7
	v_add_f32_e32 v5, 1.0, v5
	v_rcp_f32_e32 v5, v5
	v_fmac_f32_e32 v15, v3, v4
	v_add_f32_e32 v7, 1.0, v7
	v_rcp_f32_e32 v7, v7
	v_mul_f32_e32 v0, v0, v5
	v_cvt_pk_bf16_f32 v0, v0, s0
	ds_write_b16 v122, v0 offset:8448
	v_mul_f32_e32 v0, v1, v7
	v_fma_f32 v1, v2, v6, v14
	v_mul_f32_e32 v2, 0x3d372713, v1
	v_mul_f32_e32 v3, 0x3d372713, v15
	v_mul_f32_e32 v2, v1, v2
	v_mul_f32_e32 v3, v15, v3
	v_fma_f32 v2, v1, v2, v1
	v_fma_f32 v3, v15, v3, v15
	v_mul_f32_e32 v2, 0x3fcc422a, v2
	v_mul_f32_e32 v3, 0x3fcc422a, v3
	v_mul_f32_e32 v2, 0xbfb8aa3b, v2
	v_mul_f32_e32 v3, 0xbfb8aa3b, v3
	v_exp_f32_e32 v2, v2
	v_exp_f32_e32 v3, v3
	v_cvt_pk_bf16_f32 v0, v0, s0
	ds_write_b16 v122, v0 offset:8480
	v_add_f32_e32 v2, 1.0, v2
	v_add_f32_e32 v0, 1.0, v3
	v_rcp_f32_e32 v2, v2
	v_rcp_f32_e32 v0, v0
	v_lshl_add_u64 v[4:5], v[94:95], 0, s[68:69]
	v_lshlrev_b64 v[4:5], 12, v[4:5]
	v_mul_f32_e32 v1, v1, v2
	v_mul_f32_e32 v0, v15, v0
	v_cvt_pk_bf16_f32 v1, v1, s0
	v_cvt_pk_bf16_f32 v0, v0, s0
	ds_write_b16 v122, v1 offset:8512
	ds_write_b16 v122, v0 offset:8544
	s_waitcnt lgkmcnt(0)
	ds_read_b64 v[0:1], v123 offset:8448
	v_lshl_add_u64 v[2:3], v[92:93], 0, s[38:39]
	v_lshl_add_u64 v[2:3], v[2:3], 0, v[4:5]
	s_waitcnt lgkmcnt(0)
	global_store_dwordx2 v[2:3], v[0:1], off
	s_waitcnt lgkmcnt(0)
	s_cbranch_scc0 .LBB0_649
